# row phases: 64-lane sums by DPP row ops + v_permlane16/32_swap instead of six ds_bpermute round trips each
# baseline (speedup 1.0000x reference)
.LBB0_482:
	s_and_b64 vcc, exec, s[0:1]
	v_and_b32_e32 v137, 64, v198
	v_xor_b32_e32 v136, 32, v198
	v_xor_b32_e32 v135, 16, v198
	v_xor_b32_e32 v134, 8, v198
	v_xor_b32_e32 v133, 4, v198
	v_xor_b32_e32 v132, 2, v198
	v_xor_b32_e32 v130, 1, v198
	s_cbranch_vccnz .LBB0_484
	v_mov_b32_e32 v138, v118
	v_mov_b32_e32 v139, v114
	v_pk_mul_f32 v[138:139], v[138:139], v[138:139]
	v_mov_b32_e32 v140, v119
	v_mov_b32_e32 v141, v115
	v_pk_fma_f32 v[138:139], v[140:141], v[140:141], v[138:139]
	v_mov_b32_e32 v140, v116
	v_mov_b32_e32 v141, v112
	v_pk_fma_f32 v[138:139], v[140:141], v[140:141], v[138:139]
	v_mov_b32_e32 v140, v117
	v_mov_b32_e32 v141, v113
	v_pk_fma_f32 v[138:139], v[140:141], v[140:141], v[138:139]
	v_mov_b32_e32 v140, v126
	v_mov_b32_e32 v141, v122
	v_pk_mul_f32 v[140:141], v[140:141], v[140:141]
	v_mov_b32_e32 v142, v127
	v_mov_b32_e32 v143, v123
	v_pk_fma_f32 v[140:141], v[142:143], v[142:143], v[140:141]
	v_mov_b32_e32 v142, v124
	v_mov_b32_e32 v143, v120
	v_pk_fma_f32 v[140:141], v[142:143], v[142:143], v[140:141]
	v_mov_b32_e32 v142, v125
	v_mov_b32_e32 v143, v121
	v_pk_fma_f32 v[140:141], v[142:143], v[142:143], v[140:141]
	v_add_f32_e32 v138, v138, v139
	v_add_u32_e32 v139, 64, v137
	v_add_f32_e32 v138, v141, v138
	v_cmp_lt_i32_e32 vcc, v136, v139
	v_add_f32_e32 v138, v140, v138
	s_nop 1
	v_add_f32_dpp v138, v138, v138 quad_perm:[1,0,3,2] row_mask:0xf bank_mask:0xf
	s_nop 1
	v_add_f32_dpp v138, v138, v138 quad_perm:[2,3,0,1] row_mask:0xf bank_mask:0xf
	s_nop 1
	v_add_f32_dpp v138, v138, v138 row_half_mirror row_mask:0xf bank_mask:0xf
	s_nop 1
	v_add_f32_dpp v138, v138, v138 row_mirror row_mask:0xf bank_mask:0xf
	v_mov_b32_e32 v140, v138
	s_nop 1
	v_permlane16_swap_b32 v138, v140
	v_add_f32_e32 v138, v138, v140
	v_mov_b32_e32 v140, v138
	s_nop 1
	v_permlane32_swap_b32 v138, v140
	v_add_f32_e32 v138, v138, v140
	v_fmamk_f32 v138, v138, 0x3a800000, v197
	v_mul_f32_e32 v139, 0x4b800000, v138
	v_cmp_gt_f32_e32 vcc, s14, v138
	s_nop 1
	v_cndmask_b32_e32 v138, v138, v139, vcc
	v_rsq_f32_e32 v138, v138
	s_nop 0
	v_mul_f32_e32 v139, 0x45800000, v138
	v_cndmask_b32_e32 v138, v138, v139, vcc
	v_pk_mul_f32 v[140:141], v[114:115], v[138:139] op_sel_hi:[1,0]
	s_nop 0
	v_pk_mul_f32 v[140:141], v[10:11], v[140:141]
	s_waitcnt vmcnt(3)
	v_pk_fma_f32 v[94:95], v[42:43], v[140:141], v[94:95]
	v_pk_mul_f32 v[140:141], v[112:113], v[138:139] op_sel_hi:[1,0]
	s_nop 0
	v_pk_mul_f32 v[140:141], v[12:13], v[140:141]
	s_nop 0
	v_pk_fma_f32 v[96:97], v[44:45], v[140:141], v[96:97]
	v_pk_mul_f32 v[140:141], v[118:119], v[138:139] op_sel_hi:[1,0]
	s_nop 0
	v_pk_mul_f32 v[140:141], v[26:27], v[140:141]
	s_waitcnt vmcnt(2)
	v_pk_fma_f32 v[90:91], v[54:55], v[140:141], v[90:91]
	v_pk_mul_f32 v[140:141], v[116:117], v[138:139] op_sel_hi:[1,0]
	s_nop 0
	v_pk_mul_f32 v[140:141], v[28:29], v[140:141]
	s_nop 0
	v_pk_fma_f32 v[92:93], v[56:57], v[140:141], v[92:93]
	v_pk_mul_f32 v[140:141], v[122:123], v[138:139] op_sel_hi:[1,0]
	s_nop 0
	v_pk_mul_f32 v[140:141], v[38:39], v[140:141]
	s_waitcnt vmcnt(1)
	v_pk_fma_f32 v[86:87], v[66:67], v[140:141], v[86:87]
	v_pk_mul_f32 v[140:141], v[120:121], v[138:139] op_sel_hi:[1,0]
	s_nop 0
	v_pk_mul_f32 v[140:141], v[40:41], v[140:141]
	s_nop 0
	v_pk_fma_f32 v[88:89], v[68:69], v[140:141], v[88:89]
	v_pk_mul_f32 v[140:141], v[126:127], v[138:139] op_sel_hi:[1,0]
	v_pk_mul_f32 v[138:139], v[124:125], v[138:139] op_sel_hi:[1,0]
	v_pk_mul_f32 v[140:141], v[74:75], v[140:141]
	v_pk_mul_f32 v[138:139], v[76:77], v[138:139]
	s_waitcnt vmcnt(0)
	v_pk_fma_f32 v[82:83], v[78:79], v[140:141], v[82:83]
	v_pk_fma_f32 v[84:85], v[80:81], v[138:139], v[84:85]
.LBB0_484:
	v_lshlrev_b64 v[138:139], 12, v[128:129]
	v_lshl_add_u64 v[138:139], v[104:105], 0, v[138:139]
	s_and_b64 vcc, exec, s[6:7]
	s_waitcnt vmcnt(3)
	global_store_dwordx4 v[138:139], v[94:97], off sc1
	s_waitcnt vmcnt(3)
	global_store_dwordx4 v[138:139], v[90:93], off offset:1024 sc1
	s_waitcnt vmcnt(3)
	global_store_dwordx4 v[138:139], v[86:89], off offset:2048 sc1
	s_waitcnt vmcnt(3)
	global_store_dwordx4 v[138:139], v[82:85], off offset:3072 sc1
	s_cbranch_vccnz .LBB0_469
	v_mov_b32_e32 v138, v90
	v_mov_b32_e32 v139, v94
	v_pk_mul_f32 v[138:139], v[138:139], v[138:139]
	v_mov_b32_e32 v140, v91
	v_mov_b32_e32 v141, v95
	v_pk_fma_f32 v[138:139], v[140:141], v[140:141], v[138:139]
	v_mov_b32_e32 v140, v92
	v_mov_b32_e32 v141, v96
	v_pk_fma_f32 v[138:139], v[140:141], v[140:141], v[138:139]
	v_mov_b32_e32 v140, v93
	v_mov_b32_e32 v141, v97
	v_pk_fma_f32 v[138:139], v[140:141], v[140:141], v[138:139]
	v_mov_b32_e32 v140, v82
	v_mov_b32_e32 v141, v86
	v_pk_mul_f32 v[140:141], v[140:141], v[140:141]
	v_mov_b32_e32 v142, v83
	v_mov_b32_e32 v143, v87
	v_pk_fma_f32 v[140:141], v[142:143], v[142:143], v[140:141]
	v_mov_b32_e32 v142, v84
	v_mov_b32_e32 v143, v88
	v_pk_fma_f32 v[140:141], v[142:143], v[142:143], v[140:141]
	v_mov_b32_e32 v142, v85
	v_mov_b32_e32 v143, v89
	v_add_u32_e32 v137, 64, v137
	v_pk_fma_f32 v[140:141], v[142:143], v[142:143], v[140:141]
	v_add_f32_e32 v138, v138, v139
	v_cmp_lt_i32_e32 vcc, v136, v137
	v_add_f32_e32 v138, v141, v138
	v_add_f32_e32 v138, v140, v138
	v_lshlrev_b64 v[128:129], 11, v[128:129]
	v_lshl_add_u64 v[128:129], v[106:107], 0, v[128:129]
	s_nop 1
	v_add_f32_dpp v138, v138, v138 quad_perm:[1,0,3,2] row_mask:0xf bank_mask:0xf
	s_nop 1
	v_add_f32_dpp v138, v138, v138 quad_perm:[2,3,0,1] row_mask:0xf bank_mask:0xf
	s_nop 1
	v_add_f32_dpp v138, v138, v138 row_half_mirror row_mask:0xf bank_mask:0xf
	s_nop 1
	v_add_f32_dpp v138, v138, v138 row_mirror row_mask:0xf bank_mask:0xf
	v_mov_b32_e32 v140, v138
	s_nop 1
	v_permlane16_swap_b32 v138, v140
	v_add_f32_e32 v138, v138, v140
	v_mov_b32_e32 v140, v138
	s_nop 1
	v_permlane32_swap_b32 v138, v140
	v_add_f32_e32 v138, v138, v140
	v_mov_b32_e32 v130, v138
	v_fmamk_f32 v130, v130, 0x3a800000, v197
	v_mul_f32_e32 v132, 0x4b800000, v130
	v_cmp_gt_f32_e32 vcc, s14, v130
	s_nop 1
	v_cndmask_b32_e32 v130, v130, v132, vcc
	v_rsq_f32_e32 v130, v130
	s_nop 0
	v_mul_f32_e32 v132, 0x45800000, v130
	v_cndmask_b32_e32 v130, v130, v132, vcc
	v_pk_mul_f32 v[94:95], v[94:95], v[130:131] op_sel_hi:[1,0]
	v_pk_add_f32 v[132:133], v[6:7], 1.0 op_sel_hi:[1,0]
	v_pk_mul_f32 v[94:95], v[2:3], v[94:95]
	v_pk_mul_f32 v[96:97], v[96:97], v[130:131] op_sel_hi:[1,0]
	v_pk_fma_f32 v[94:95], v[132:133], v[94:95], v[14:15]
	v_pk_add_f32 v[132:133], v[8:9], 1.0 op_sel_hi:[1,0]
	v_pk_mul_f32 v[96:97], v[4:5], v[96:97]
	v_cvt_pk_bf16_f32 v94, v94, v95
	v_pk_fma_f32 v[96:97], v[132:133], v[96:97], v[16:17]
	v_pk_mul_f32 v[90:91], v[90:91], v[130:131] op_sel_hi:[1,0]
	v_cvt_pk_bf16_f32 v95, v96, v97
	global_store_dwordx2 v[128:129], v[94:95], off
	v_pk_add_f32 v[94:95], v[22:23], 1.0 op_sel_hi:[1,0]
	v_pk_mul_f32 v[90:91], v[18:19], v[90:91]
	v_pk_mul_f32 v[92:93], v[92:93], v[130:131] op_sel_hi:[1,0]
	v_pk_fma_f32 v[90:91], v[94:95], v[90:91], v[30:31]
	v_pk_add_f32 v[94:95], v[24:25], 1.0 op_sel_hi:[1,0]
	v_pk_mul_f32 v[92:93], v[20:21], v[92:93]
	v_cvt_pk_bf16_f32 v90, v90, v91
	v_pk_fma_f32 v[92:93], v[94:95], v[92:93], v[32:33]
	v_pk_mul_f32 v[86:87], v[86:87], v[130:131] op_sel_hi:[1,0]
	v_cvt_pk_bf16_f32 v91, v92, v93
	global_store_dwordx2 v[128:129], v[90:91], off offset:512
	v_pk_add_f32 v[90:91], v[46:47], 1.0 op_sel_hi:[1,0]
	v_pk_mul_f32 v[86:87], v[34:35], v[86:87]
	v_pk_mul_f32 v[88:89], v[88:89], v[130:131] op_sel_hi:[1,0]
	v_pk_fma_f32 v[86:87], v[90:91], v[86:87], v[50:51]
	v_pk_add_f32 v[90:91], v[48:49], 1.0 op_sel_hi:[1,0]
	v_pk_mul_f32 v[88:89], v[36:37], v[88:89]
	v_cvt_pk_bf16_f32 v86, v86, v87
	v_pk_fma_f32 v[88:89], v[90:91], v[88:89], v[52:53]
	v_pk_mul_f32 v[82:83], v[82:83], v[130:131] op_sel_hi:[1,0]
	v_cvt_pk_bf16_f32 v87, v88, v89
	global_store_dwordx2 v[128:129], v[86:87], off offset:1024
	v_pk_add_f32 v[86:87], v[62:63], 1.0 op_sel_hi:[1,0]
	v_pk_mul_f32 v[82:83], v[58:59], v[82:83]
	v_pk_mul_f32 v[84:85], v[84:85], v[130:131] op_sel_hi:[1,0]
	v_pk_fma_f32 v[82:83], v[86:87], v[82:83], v[70:71]
	v_pk_add_f32 v[86:87], v[64:65], 1.0 op_sel_hi:[1,0]
	v_pk_mul_f32 v[84:85], v[60:61], v[84:85]
	v_cvt_pk_bf16_f32 v82, v82, v83
	v_pk_fma_f32 v[84:85], v[86:87], v[84:85], v[72:73]
	s_nop 0
	v_cvt_pk_bf16_f32 v83, v84, v85
	global_store_dwordx2 v[128:129], v[82:83], off offset:1536
	s_branch .LBB0_469
